# c32: SSD item setup loads both halves of the segment's dt values together (one global round trip per item)
# baseline (speedup 1.0000x reference)
; template <int PASS>
; __device__ void ssd_item(const Params& p, int item, int l, unsigned char* smem) {
;     ...
;     const float Aneg = -__expf(p.a_log[l * 16 + dir * 8 + h]);
;     const float Dh = p.d_skip[l * 8 + h];
;     __syncthreads();
;     f32x4 S[8];
; #pragma unroll
;     for (int nt = 0; nt < 8; ++nt) S[nt] = (f32x4){0.f, 0.f, 0.f, 0.f};
;     const int ibase = item & ~15;
;     if (PASS == 3) {
;         if (dir == 0) {
;             for (int e = 0; e < seg; ++e) { const float dc = __expf(SEGT[ibase + e]); const f32x4* src = (const f32x4*)(ST + (size_t)(ibase + e) * 8192);
; #pragma unroll
;                 for (int nt = 0; nt < 8; ++nt) S[nt] = S[nt] * dc + src[(w * 8 + nt) * 64 + lane]; }
;         } else {
;             for (int e = NSEG - 1; e > seg; --e) { const float dc = __expf(SEGT[ibase + e]); const f32x4* src = (const f32x4*)(ST + (size_t)(ibase + e) * 8192);
; #pragma unroll
;                 for (int nt = 0; nt < 8; ++nt) S[nt] = S[nt] * dc + src[(w * 8 + nt) * 64 + lane]; }
;         }
; #pragma unroll
;         for (int nt = 0; nt < 8; ++nt) st4bf(Sb + (16 * w + idx) * 136 + 16 * nt + 4 * kq, S[nt]);
;     }
;     float* s_dta = (float*)(smem + SS_DTA);
; #pragma unroll
;     for (int i = 0; i < SEGLEN / 256; ++i) {
;         const int e = tid + 256 * i, l32 = lane & 31;
;         const float dtv = DT[((size_t)b * SEQ + seg * SEGLEN + e) * 16 + dir * 8 + h], av = dtv * Aneg;
;         float pre = av;
; #pragma unroll
;         for (int o = 1; o < 32; o <<= 1) { const float t = __shfl_up(pre, o, 32); if (l32 >= o) pre += t; }
;         const float tot = __shfl(pre, 31, 32);
;         const float cc = dir ? (tot - pre + av) : pre;
;         s_dta[e] = dtv; s_cA[e] = cc; s_rsA[e] = __expf(cc); s_wlA[e] = dtv * __expf(tot - cc);
;         if (l32 == 0) s_totA[e >> 5] = tot;
;     }
;     float segtot = 0.f;
;     const size_t tokb = (size_t)b * SEQ;
;     const unsigned char* xb_ = (const unsigned char*)((const bf16_t*)(p.ws + WS_XBCC) + tokb * 1024);
;     unsigned soff[5];
; #pragma unroll
;     for (int i = 0; i < 5; ++i) { const int u = tid + 256 * i, lrow = u / 40, ci = u % 40;
;         const int scol = ci < 8 ? h * 64 + ci * 8 : (ci < 24 ? 512 + grp * 128 + (ci * 8 - 64) : 768 + grp * 128 + (ci * 8 - 192));
;         soff[i] = (unsigned)((lrow * 1024 + scol) * 2); }
.LBB0_691:
	s_bfe_u32 s23, s62, 0x10007
	s_lshl_b32 s12, s23, 3
	v_readlane_b32 s24, v255, 28
	s_bfe_u32 s22, s62, 0x30004
	s_or_b32 s12, s12, s24
	v_readlane_b32 s25, v255, 29
	s_or_b32 s12, s12, s22
	s_ashr_i32 s48, s62, 8
	s_lshl_b64 s[24:25], s[12:13], 2
	s_add_u32 s24, s58, s24
	s_addc_u32 s25, s59, s25
	s_and_b32 s12, s62, 15
	s_cmp_eq_u32 s23, 0
	v_mov_b32_e32 v52, v212
	s_cselect_b64 vcc, -1, 0
	s_ashr_i32 s49, s48, 31
	global_load_dword v2, v81, s[24:25]
	s_lshl_b64 s[46:47], s[48:49], 13
	s_lshl_b32 s24, s12, 9
	s_or_b32 s46, s46, s24
	s_lshl_b32 s23, s23, 5
	s_add_u32 s23, s9, s23
	s_addc_u32 s24, s11, 0
	s_lshl_b32 s25, s22, 2
	v_ashrrev_i32_e32 v53, 31, v52
	s_add_u32 s50, s23, s25
	v_lshl_add_u64 v[0:1], s[46:47], 0, v[52:53]
	s_addc_u32 s51, s24, 0
	v_lshlrev_b64 v[0:1], 6, v[0:1]
	v_lshl_add_u64 v[0:1], s[50:51], 0, v[0:1]
	s_mov_b64 s[98:99], 0x4000
	v_lshl_add_u64 v[206:207], v[0:1], 0, s[98:99]
	s_barrier
	global_load_dword v1, v[0:1], off
	global_load_dword v207, v[206:207], off
	v_and_b32_e32 v0, 0x60, v216
	v_add_u32_e32 v3, -1, v216
	v_cmp_lt_i32_e64 s[36:37], v3, v0
	v_add_u32_e32 v4, -2, v216
	v_and_b32_e32 v9, 31, v52
	v_cndmask_b32_e64 v3, v3, v216, s[36:37]
	v_lshlrev_b32_e32 v3, 2, v3
	v_cmp_lt_i32_e64 s[36:37], v4, v0
	v_cmp_gt_u32_e64 s[44:45], 16, v9
	s_waitcnt vmcnt(1)
	v_mul_f32_e32 v2, 0x3fb8aa3b, v2
	v_exp_f32_e32 v2, v2
	v_cndmask_b32_e64 v4, v4, v216, s[36:37]
	v_cmp_eq_u32_e64 s[36:37], 0, v9
	v_lshlrev_b32_e32 v4, 2, v4
	s_waitcnt vmcnt(0)
	v_mul_f32_e64 v5, v1, -v2
	ds_bpermute_b32 v6, v3, v5
	s_waitcnt lgkmcnt(0)
	v_fma_f32 v6, v1, -v2, v6
	v_cndmask_b32_e64 v6, v6, v5, s[36:37]
	ds_bpermute_b32 v7, v4, v6
	v_add_u32_e32 v5, -4, v216
	v_cmp_lt_i32_e64 s[38:39], v5, v0
	s_waitcnt lgkmcnt(0)
	v_add_f32_e32 v7, v6, v7
	v_cndmask_b32_e64 v5, v5, v216, s[38:39]
	v_cmp_gt_u32_e64 s[38:39], 2, v9
	v_lshlrev_b32_e32 v5, 2, v5
	s_nop 0
	v_cndmask_b32_e64 v7, v7, v6, s[38:39]
	ds_bpermute_b32 v8, v5, v7
	v_add_u32_e32 v6, -8, v216
	v_cmp_lt_i32_e64 s[40:41], v6, v0
	s_waitcnt lgkmcnt(0)
	v_add_f32_e32 v8, v7, v8
	v_cndmask_b32_e64 v6, v6, v216, s[40:41]
	v_cmp_gt_u32_e64 s[40:41], 4, v9
	v_lshlrev_b32_e32 v6, 2, v6
	s_nop 0
	v_cndmask_b32_e64 v8, v8, v7, s[40:41]
	ds_bpermute_b32 v10, v6, v8
	v_add_u32_e32 v7, -16, v216
	v_cmp_lt_i32_e64 s[42:43], v7, v0
	s_nop 1
	v_cndmask_b32_e64 v0, v7, v216, s[42:43]
	v_lshlrev_b32_e32 v7, 2, v0
	s_waitcnt lgkmcnt(0)
	v_add_f32_e32 v0, v8, v10
	v_cmp_gt_u32_e64 s[42:43], 8, v9
	s_nop 1
	v_cndmask_b32_e64 v0, v0, v8, s[42:43]
	ds_bpermute_b32 v10, v7, v0
	v_lshl_or_b32 v8, v216, 2, v229
	s_waitcnt lgkmcnt(0)
	v_add_f32_e32 v10, v0, v10
	v_cndmask_b32_e64 v9, v10, v0, s[44:45]
	ds_bpermute_b32 v0, v8, v9
	s_waitcnt lgkmcnt(0)
	v_sub_f32_e32 v10, v0, v9
	v_fma_f32 v10, v1, -v2, v10
	v_cndmask_b32_e32 v10, v10, v9, vcc
	v_mul_f32_e32 v9, 0x3fb8aa3b, v10
	v_sub_f32_e32 v11, v0, v10
	v_exp_f32_e32 v12, v9
	v_mul_f32_e32 v9, 0x3fb8aa3b, v11
	v_exp_f32_e32 v11, v9
	v_lshl_add_u32 v9, v52, 2, v54
	ds_write2st64_b32 v9, v10, v12 offset0:182 offset1:190
	v_mul_f32_e32 v10, v1, v11
	ds_write2st64_b32 v9, v10, v1 offset0:198 offset1:216
	s_and_saveexec_b64 s[52:53], s[36:37]
	v_ashrrev_i32_e32 v1, 3, v52
	v_add_u32_e32 v1, v54, v1
	ds_write_b32 v1, v0 offset:54272
	s_or_b64 exec, exec, s[52:53]
	v_add_u32_e32 v0, 0x100, v52
	v_ashrrev_i32_e32 v1, 31, v0
	v_lshl_add_u64 v[10:11], s[46:47], 0, v[0:1]
	v_lshlrev_b64 v[10:11], 6, v[10:11]
	v_lshl_add_u64 v[10:11], s[50:51], 0, v[10:11]
	v_mov_b32_e32 v10, v207
	s_waitcnt vmcnt(0)
	v_mul_f32_e64 v1, v10, -v2
	ds_bpermute_b32 v3, v3, v1
	s_waitcnt lgkmcnt(0)
	v_fma_f32 v3, v10, -v2, v3
	v_cndmask_b32_e64 v1, v3, v1, s[36:37]
	ds_bpermute_b32 v3, v4, v1
	s_waitcnt lgkmcnt(0)
	v_add_f32_e32 v3, v1, v3
	v_cndmask_b32_e64 v1, v3, v1, s[38:39]
	ds_bpermute_b32 v3, v5, v1
	s_waitcnt lgkmcnt(0)
	v_add_f32_e32 v3, v1, v3
	v_cndmask_b32_e64 v1, v3, v1, s[40:41]
	ds_bpermute_b32 v3, v6, v1
	s_waitcnt lgkmcnt(0)
	v_add_f32_e32 v3, v1, v3
	v_cndmask_b32_e64 v1, v3, v1, s[42:43]
	ds_bpermute_b32 v3, v7, v1
	s_waitcnt lgkmcnt(0)
	v_add_f32_e32 v3, v1, v3
	v_cndmask_b32_e64 v3, v3, v1, s[44:45]
	ds_bpermute_b32 v1, v8, v3
	s_waitcnt lgkmcnt(0)
	v_sub_f32_e32 v4, v1, v3
	v_fma_f32 v2, v10, -v2, v4
	v_cndmask_b32_e32 v2, v2, v3, vcc
	v_sub_f32_e32 v4, v1, v2
	v_mul_f32_e32 v3, 0x3fb8aa3b, v2
	v_mul_f32_e32 v4, 0x3fb8aa3b, v4
	v_exp_f32_e32 v3, v3
	v_exp_f32_e32 v4, v4
	ds_write2st64_b32 v9, v2, v3 offset0:186 offset1:194
	v_mul_f32_e32 v2, v10, v4
	ds_write2st64_b32 v9, v2, v10 offset0:202 offset1:220
	s_and_saveexec_b64 s[38:39], s[36:37]
	v_ashrrev_i32_e32 v2, 3, v0
	v_add_u32_e32 v2, v54, v2
	ds_write_b32 v2, v1 offset:54272
	s_or_b64 exec, exec, s[38:39]
	v_mul_hi_i32 v1, v52, s68
	v_lshrrev_b32_e32 v2, 31, v1
	v_ashrrev_i32_e32 v1, 4, v1
	v_add_u32_e32 v53, v1, v2
	s_lshl_b32 s23, s22, 5
	v_mul_lo_u32 v1, v53, 40
	s_and_b32 s23, s23, 0x80
	v_sub_u32_e32 v1, v52, v1
	s_or_b32 s24, s23, 0x240
	s_addk_i32 s23, 0x1c0
	v_cmp_lt_i32_e64 s[36:37], 7, v1
	s_and_saveexec_b64 s[26:27], s[36:37]
	s_xor_b64 s[40:41], exec, s[26:27]
	s_cbranch_execz .LBB0_701
	v_cmp_lt_u32_e64 s[38:39], 23, v1
	v_lshlrev_b32_e32 v3, 3, v1
	s_and_saveexec_b64 s[26:27], s[38:39]
	s_xor_b64 s[38:39], exec, s[26:27]
	v_add_u32_e32 v2, s24, v3
	s_andn2_saveexec_b64 s[38:39], s[38:39]
	v_add_u32_e32 v2, s23, v3
	s_or_b64 exec, exec, s[38:39]

; __device__ __forceinline__ void st4bf(bf16_t* dst, f32x4 v) { u32x2 pk; pk.x = pk2(v.x, v.y); pk.y = pk2(v.z, v.w); *(u32x2*)dst = pk; }
; template <int PASS>
; __device__ void ssd_item(const Params& p, int item, int l, unsigned char* smem) {
;     ...
;         for (int nt = 0; nt < 8; ++nt) st4bf(Sb + (16 * w + idx) * 136 + 16 * nt + 4 * kq, S[nt]);
;     }
;     float* s_dta = (float*)(smem + SS_DTA);
; #pragma unroll
;     for (int i = 0; i < SEGLEN / 256; ++i) {
;         const int e = tid + 256 * i, l32 = lane & 31;
;         const float dtv = DT[((size_t)b * SEQ + seg * SEGLEN + e) * 16 + dir * 8 + h], av = dtv * Aneg;
;         float pre = av;
; #pragma unroll
;         for (int o = 1; o < 32; o <<= 1) { const float t = __shfl_up(pre, o, 32); if (l32 >= o) pre += t; }
;         const float tot = __shfl(pre, 31, 32);
;         const float cc = dir ? (tot - pre + av) : pre;
;         s_dta[e] = dtv; s_cA[e] = cc; s_rsA[e] = __expf(cc); s_wlA[e] = dtv * __expf(tot - cc);
;         if (l32 == 0) s_totA[e >> 5] = tot;
;     }
.LBB0_868:
	s_waitcnt vmcnt(1)
	v_mul_f32_e32 v34, 0x3fb8aa3b, v37
	v_exp_f32_e32 v40, v34
	v_and_b32_e32 v53, 15, v32
	v_lshlrev_b32_e32 v34, 4, v33
	v_or_b32_e32 v33, v34, v53
	v_lshrrev_b32_e32 v35, 4, v36
	s_ashr_i32 s48, s19, 8
	v_mad_u64_u32 v[36:37], s[22:23], v33, s0, v[52:53]
	v_lshl_add_u32 v33, v35, 3, v36
	s_ashr_i32 s49, s48, 31
	v_cvt_pk_bf16_f32 v38, v0, v1
	v_cvt_pk_bf16_f32 v39, v2, v3
	v_cvt_pk_bf16_f32 v42, v4, v5
	v_cvt_pk_bf16_f32 v43, v6, v7
	v_add_u32_e32 v57, 0x7000, v33
	s_lshl_b64 s[94:95], s[48:49], 13
	s_lshl_b32 s12, s12, 9
	ds_write2_b64 v57, v[38:39], v[42:43] offset0:64 offset1:68
	v_cvt_pk_bf16_f32 v38, v8, v9
	v_cvt_pk_bf16_f32 v39, v10, v11
	v_cvt_pk_bf16_f32 v42, v12, v13
	v_cvt_pk_bf16_f32 v43, v14, v15
	s_or_b32 s46, s94, s12
	s_lshl_b32 s21, s21, 2
	ds_write2_b64 v57, v[38:39], v[42:43] offset0:72 offset1:76
	v_cvt_pk_bf16_f32 v38, v16, v17
	v_cvt_pk_bf16_f32 v39, v18, v19
	v_cvt_pk_bf16_f32 v42, v20, v21
	v_cvt_pk_bf16_f32 v43, v22, v23
	s_add_u32 s21, s9, s21
	ds_write2_b64 v57, v[38:39], v[42:43] offset0:80 offset1:84
	v_cvt_pk_bf16_f32 v38, v24, v25
	v_cvt_pk_bf16_f32 v39, v26, v27
	v_cvt_pk_bf16_f32 v42, v28, v29
	v_cvt_pk_bf16_f32 v43, v30, v31
	s_mov_b32 s47, s95
	s_addc_u32 s22, s16, 0
	s_lshl_b32 s23, s20, 2
	v_ashrrev_i32_e32 v33, 31, v32
	ds_write2_b64 v57, v[38:39], v[42:43] offset0:88 offset1:92
	s_add_u32 s50, s21, s23
	v_lshl_add_u64 v[38:39], s[46:47], 0, v[32:33]
	s_addc_u32 s51, s22, 0
	v_lshlrev_b64 v[38:39], 6, v[38:39]
	v_lshl_add_u64 v[38:39], s[50:51], 0, v[38:39]
	global_load_dword v33, v[38:39], off
	s_mov_b64 s[98:99], 0x4000
	v_lshl_add_u64 v[206:207], v[38:39], 0, s[98:99]
	global_load_dword v207, v[206:207], off
	v_and_b32_e32 v45, 0x60, v216
	v_add_u32_e32 v39, -1, v216
	v_cmp_lt_i32_e64 s[38:39], v39, v45
	v_and_b32_e32 v46, 31, v32
	v_cmp_eq_u32_e32 vcc, 0, v46
	v_cndmask_b32_e64 v39, v39, v216, s[38:39]
	v_lshlrev_b32_e32 v41, 2, v39
	v_lshl_or_b32 v37, v216, 2, v229
	s_waitcnt vmcnt(0)
	v_mul_f32_e64 v38, v33, -v40
	ds_bpermute_b32 v39, v41, v38
	s_waitcnt lgkmcnt(0)
	v_fma_f32 v39, v33, -v40, v39
	v_cndmask_b32_e32 v38, v39, v38, vcc
	v_add_u32_e32 v39, -2, v216
	v_cmp_lt_i32_e64 s[38:39], v39, v45
	s_nop 1
	v_cndmask_b32_e64 v39, v39, v216, s[38:39]
	v_lshlrev_b32_e32 v42, 2, v39
	ds_bpermute_b32 v39, v42, v38
	v_cmp_gt_u32_e64 s[38:39], 2, v46
	s_waitcnt lgkmcnt(0)
	v_add_f32_e32 v39, v38, v39
	v_cndmask_b32_e64 v38, v39, v38, s[38:39]
	v_add_u32_e32 v39, -4, v216
	v_cmp_lt_i32_e64 s[40:41], v39, v45
	s_nop 1
	v_cndmask_b32_e64 v39, v39, v216, s[40:41]
	v_lshlrev_b32_e32 v43, 2, v39
	ds_bpermute_b32 v39, v43, v38
	v_cmp_gt_u32_e64 s[40:41], 4, v46
	s_waitcnt lgkmcnt(0)
	v_add_f32_e32 v39, v38, v39
	v_cndmask_b32_e64 v38, v39, v38, s[40:41]
	v_add_u32_e32 v39, -8, v216
	v_cmp_lt_i32_e64 s[42:43], v39, v45
	s_nop 1
	v_cndmask_b32_e64 v39, v39, v216, s[42:43]
	v_lshlrev_b32_e32 v44, 2, v39
	ds_bpermute_b32 v39, v44, v38
	v_cmp_gt_u32_e64 s[42:43], 8, v46
	s_waitcnt lgkmcnt(0)
	v_add_f32_e32 v39, v38, v39
	v_cndmask_b32_e64 v38, v39, v38, s[42:43]
	v_add_u32_e32 v39, -16, v216
	v_cmp_lt_i32_e64 s[44:45], v39, v45
	s_nop 1
	v_cndmask_b32_e64 v39, v39, v216, s[44:45]
	v_lshlrev_b32_e32 v45, 2, v39
	ds_bpermute_b32 v39, v45, v38
	v_cmp_gt_u32_e64 s[44:45], 16, v46
	s_waitcnt lgkmcnt(0)
	v_add_f32_e32 v39, v38, v39
	v_cndmask_b32_e64 v39, v39, v38, s[44:45]
	ds_bpermute_b32 v38, v37, v39
	s_waitcnt lgkmcnt(0)
	v_sub_f32_e32 v46, v38, v39
	v_fma_f32 v46, v33, -v40, v46
	v_cndmask_b32_e64 v39, v46, v39, s[36:37]
	v_mul_f32_e32 v47, 0x3fb8aa3b, v39
	v_exp_f32_e32 v47, v47
	v_lshl_add_u32 v46, v32, 2, v52
	ds_write2st64_b32 v46, v39, v47 offset0:182 offset1:190
	v_sub_f32_e32 v39, v38, v39
	v_mul_f32_e32 v39, 0x3fb8aa3b, v39
	v_exp_f32_e32 v39, v39
	s_nop 0
	v_mul_f32_e32 v39, v33, v39
	ds_write2st64_b32 v46, v39, v33 offset0:198 offset1:216
	v_ashrrev_i32_e32 v33, 3, v32
	s_and_saveexec_b64 s[52:53], vcc
	v_add_u32_e32 v39, v52, v33
	ds_write_b32 v39, v38 offset:54272
	s_or_b64 exec, exec, s[52:53]
	v_add_u32_e32 v38, 0x100, v32
	v_ashrrev_i32_e32 v39, 31, v38
	v_lshl_add_u64 v[48:49], s[46:47], 0, v[38:39]
	v_lshlrev_b64 v[48:49], 6, v[48:49]
	v_lshl_add_u64 v[48:49], s[50:51], 0, v[48:49]
	v_mov_b32_e32 v39, v207
	s_waitcnt vmcnt(0)
	v_mul_f32_e64 v47, v39, -v40
	ds_bpermute_b32 v41, v41, v47
	s_waitcnt lgkmcnt(0)
	v_fma_f32 v41, v39, -v40, v41
	v_cndmask_b32_e32 v41, v41, v47, vcc
	ds_bpermute_b32 v42, v42, v41
	s_waitcnt lgkmcnt(0)
	v_add_f32_e32 v42, v41, v42
	v_cndmask_b32_e64 v41, v42, v41, s[38:39]
	ds_bpermute_b32 v42, v43, v41
	s_waitcnt lgkmcnt(0)
	v_add_f32_e32 v42, v41, v42
	v_cndmask_b32_e64 v41, v42, v41, s[40:41]
	ds_bpermute_b32 v42, v44, v41
	s_waitcnt lgkmcnt(0)
	v_add_f32_e32 v42, v41, v42
	v_cndmask_b32_e64 v41, v42, v41, s[42:43]
	ds_bpermute_b32 v42, v45, v41
	s_waitcnt lgkmcnt(0)
	v_add_f32_e32 v42, v41, v42
	v_cndmask_b32_e64 v41, v42, v41, s[44:45]
	ds_bpermute_b32 v37, v37, v41
	s_waitcnt lgkmcnt(0)
	v_sub_f32_e32 v42, v37, v41
	v_fma_f32 v40, v39, -v40, v42
	v_cndmask_b32_e64 v40, v40, v41, s[36:37]
	v_sub_f32_e32 v42, v37, v40
	v_mul_f32_e32 v41, 0x3fb8aa3b, v40
	v_mul_f32_e32 v42, 0x3fb8aa3b, v42
	v_exp_f32_e32 v41, v41
	v_exp_f32_e32 v42, v42
	ds_write2st64_b32 v46, v40, v41 offset0:186 offset1:194
	v_mul_f32_e32 v40, v39, v42
	ds_write2st64_b32 v46, v40, v39 offset0:202 offset1:220
	s_and_saveexec_b64 s[38:39], vcc
	v_ashrrev_i32_e32 v39, 3, v38
	v_add_u32_e32 v39, v52, v39
	ds_write_b32 v39, v37 offset:54272
	s_or_b64 exec, exec, s[38:39]
	v_mul_hi_i32 v37, v32, s68
	v_lshrrev_b32_e32 v39, 31, v37
	v_ashrrev_i32_e32 v37, 4, v37
	v_add_u32_e32 v62, v37, v39
	s_lshl_b32 s21, s20, 5
	v_mul_lo_u32 v37, v62, 40
	s_and_b32 s22, s21, 0x80
	v_sub_u32_e32 v37, v32, v37
	s_or_b32 s23, s22, 0x240
	s_addk_i32 s22, 0x1c0
	v_cmp_lt_i32_e64 s[38:39], 7, v37
	s_and_saveexec_b64 s[24:25], s[38:39]
	s_xor_b64 s[40:41], exec, s[24:25]
	s_cbranch_execz .LBB0_878
	v_cmp_lt_u32_e32 vcc, 23, v37
	v_lshlrev_b32_e32 v40, 3, v37
	s_and_saveexec_b64 s[24:25], vcc
	s_xor_b64 s[42:43], exec, s[24:25]
	v_add_u32_e32 v39, s23, v40
	s_andn2_saveexec_b64 s[42:43], s[42:43]
	v_add_u32_e32 v39, s22, v40
	s_or_b64 exec, exec, s[42:43]
